# M2 prelude rewritten: loads up front, DPP scans, wave_shr neighbours, v_readlane carries (was 30 serial ds_bpermute)
# baseline (speedup 1.0000x reference)
.LBB0_45:
	s_ashr_i32 s64, s66, 14
	s_and_b32 s0, s66, 0x3e00
	s_lshl_b32 s46, s64, 7
	s_barrier
	s_mov_b64 s[14:15], exec
	v_readlane_b32 s2, v254, 39
	v_readlane_b32 s3, v254, 40
	s_and_b64 s[2:3], s[14:15], s[2:3]
	s_mov_b64 exec, s[2:3]
	s_cbranch_execz .LBB0_51
	v_or_b32_e32 v0, s46, v77
	v_readlane_b32 s2, v254, 49
	v_readlane_b32 s3, v254, 50
	v_readlane_b32 s6, v254, 51
	v_readlane_b32 s7, v254, 52
	v_readlane_b32 s8, v254, 53
	v_readlane_b32 s9, v254, 54
	v_lshlrev_b32_e32 v1, 2, v0
	s_nop 4
	global_load_dword v11, v1, s[2:3]
	global_load_dword v9, v1, s[6:7]
	global_load_dword v10, v1, s[2:3] offset:256
	global_load_dword v8, v1, s[6:7] offset:256
	s_waitcnt vmcnt(3)
	v_mov_b32_e32 v4, v11
	s_nop 1
	v_add_f32_dpp v4, v4, v4 row_shr:1 row_mask:0xf bank_mask:0xf
	s_nop 1
	v_add_f32_dpp v4, v4, v4 row_shr:2 row_mask:0xf bank_mask:0xf
	s_nop 1
	v_add_f32_dpp v4, v4, v4 row_shr:4 row_mask:0xf bank_mask:0xf
	s_nop 1
	v_add_f32_dpp v4, v4, v4 row_shr:8 row_mask:0xf bank_mask:0xf
	s_nop 1
	v_add_f32_dpp v4, v4, v4 row_bcast:15 row_mask:0xa bank_mask:0xf
	s_nop 1
	v_add_f32_dpp v4, v4, v4 row_bcast:31 row_mask:0xc bank_mask:0xf
	v_mov_b32_e32 v5, 0
	s_nop 1
	v_mov_b32_dpp v5, v4 wave_shr:1 row_mask:0xf bank_mask:0xf
	s_waitcnt vmcnt(2)
	v_sub_f32_e32 v6, v9, v5
	s_nop 1
	v_max_f32_dpp v6, v6, v6 row_shr:1 row_mask:0xf bank_mask:0xf
	s_nop 1
	v_max_f32_dpp v6, v6, v6 row_shr:2 row_mask:0xf bank_mask:0xf
	s_nop 1
	v_max_f32_dpp v6, v6, v6 row_shr:4 row_mask:0xf bank_mask:0xf
	s_nop 1
	v_max_f32_dpp v6, v6, v6 row_shr:8 row_mask:0xf bank_mask:0xf
	s_nop 1
	v_max_f32_dpp v6, v6, v6 row_bcast:15 row_mask:0xa bank_mask:0xf
	s_nop 1
	v_max_f32_dpp v6, v6, v6 row_bcast:31 row_mask:0xc bank_mask:0xf
	v_max_f32_e32 v6, 0, v6
	v_mov_b32_e32 v7, 0
	s_nop 1
	v_mov_b32_dpp v7, v6 wave_shr:1 row_mask:0xf bank_mask:0xf
	v_add_f32_e32 v12, v5, v7
	v_add_f32_e32 v13, v4, v6
	v_add_f32_e32 v14, v11, v12
	v_sub_f32_e32 v14, v14, v13
	v_add_f32_e32 v15, v11, v9
	v_sub_f32_e32 v15, v15, v13
	v_mul_f32_e32 v18, 0x3fb8aa3b, v14
	v_fma_f32 v19, v14, s62, -v18
	v_rndne_f32_e32 v20, v18
	v_fmac_f32_e32 v19, 0x32a5705f, v14
	v_sub_f32_e32 v18, v18, v20
	v_add_f32_e32 v18, v18, v19
	v_exp_f32_e32 v18, v18
	v_cvt_i32_f32_e32 v20, v20
	v_cmp_ngt_f32_e32 vcc, s72, v14
	v_ldexp_f32 v18, v18, v20
	s_nop 0
	v_cndmask_b32_e32 v18, 0, v18, vcc
	v_cmp_nlt_f32_e32 vcc, s73, v14
	s_nop 1
	v_cndmask_b32_e32 v16, v244, v18, vcc
	v_mul_f32_e32 v18, 0x3fb8aa3b, v15
	v_fma_f32 v19, v15, s62, -v18
	v_rndne_f32_e32 v20, v18
	v_fmac_f32_e32 v19, 0x32a5705f, v15
	v_sub_f32_e32 v18, v18, v20
	v_add_f32_e32 v18, v18, v19
	v_exp_f32_e32 v18, v18
	v_cvt_i32_f32_e32 v20, v20
	v_cmp_ngt_f32_e32 vcc, s72, v15
	v_ldexp_f32 v18, v18, v20
	s_nop 0
	v_cndmask_b32_e32 v18, 0, v18, vcc
	v_cmp_nlt_f32_e32 vcc, s73, v15
	s_nop 1
	v_cndmask_b32_e32 v17, v244, v18, vcc
	ds_write2st64_b32 v78, v16, v17 offset1:2
	s_cmp_lg_u32 s0, 0
	s_cbranch_scc1 .Lm2p_a
	global_store_dword v1, v12, s[8:9]
.Lm2p_a:
	v_readlane_b32 s4, v4, 63
	v_readlane_b32 s5, v6, 63
	s_waitcnt vmcnt(0)
	v_mov_b32_e32 v4, v10
	s_nop 1
	v_add_f32_dpp v4, v4, v4 row_shr:1 row_mask:0xf bank_mask:0xf
	s_nop 1
	v_add_f32_dpp v4, v4, v4 row_shr:2 row_mask:0xf bank_mask:0xf
	s_nop 1
	v_add_f32_dpp v4, v4, v4 row_shr:4 row_mask:0xf bank_mask:0xf
	s_nop 1
	v_add_f32_dpp v4, v4, v4 row_shr:8 row_mask:0xf bank_mask:0xf
	s_nop 1
	v_add_f32_dpp v4, v4, v4 row_bcast:15 row_mask:0xa bank_mask:0xf
	s_nop 1
	v_add_f32_dpp v4, v4, v4 row_bcast:31 row_mask:0xc bank_mask:0xf
	v_add_f32_e32 v4, s4, v4
	v_mov_b32_e32 v5, s4
	s_nop 1
	v_mov_b32_dpp v5, v4 wave_shr:1 row_mask:0xf bank_mask:0xf
	v_sub_f32_e32 v6, v8, v5
	s_nop 1
	v_max_f32_dpp v6, v6, v6 row_shr:1 row_mask:0xf bank_mask:0xf
	s_nop 1
	v_max_f32_dpp v6, v6, v6 row_shr:2 row_mask:0xf bank_mask:0xf
	s_nop 1
	v_max_f32_dpp v6, v6, v6 row_shr:4 row_mask:0xf bank_mask:0xf
	s_nop 1
	v_max_f32_dpp v6, v6, v6 row_shr:8 row_mask:0xf bank_mask:0xf
	s_nop 1
	v_max_f32_dpp v6, v6, v6 row_bcast:15 row_mask:0xa bank_mask:0xf
	s_nop 1
	v_max_f32_dpp v6, v6, v6 row_bcast:31 row_mask:0xc bank_mask:0xf
	v_max_f32_e32 v6, s5, v6
	v_mov_b32_e32 v7, s5
	s_nop 1
	v_mov_b32_dpp v7, v6 wave_shr:1 row_mask:0xf bank_mask:0xf
	v_add_f32_e32 v12, v5, v7
	v_add_f32_e32 v13, v4, v6
	v_add_f32_e32 v14, v10, v12
	v_sub_f32_e32 v14, v14, v13
	v_add_f32_e32 v15, v10, v8
	v_sub_f32_e32 v15, v15, v13
	v_mul_f32_e32 v18, 0x3fb8aa3b, v14
	v_fma_f32 v19, v14, s62, -v18
	v_rndne_f32_e32 v20, v18
	v_fmac_f32_e32 v19, 0x32a5705f, v14
	v_sub_f32_e32 v18, v18, v20
	v_add_f32_e32 v18, v18, v19
	v_exp_f32_e32 v18, v18
	v_cvt_i32_f32_e32 v20, v20
	v_cmp_ngt_f32_e32 vcc, s72, v14
	v_ldexp_f32 v18, v18, v20
	s_nop 0
	v_cndmask_b32_e32 v18, 0, v18, vcc
	v_cmp_nlt_f32_e32 vcc, s73, v14
	s_nop 1
	v_cndmask_b32_e32 v16, v244, v18, vcc
	v_mul_f32_e32 v18, 0x3fb8aa3b, v15
	v_fma_f32 v19, v15, s62, -v18
	v_rndne_f32_e32 v20, v18
	v_fmac_f32_e32 v19, 0x32a5705f, v15
	v_sub_f32_e32 v18, v18, v20
	v_add_f32_e32 v18, v18, v19
	v_exp_f32_e32 v18, v18
	v_cvt_i32_f32_e32 v20, v20
	v_cmp_ngt_f32_e32 vcc, s72, v15
	v_ldexp_f32 v18, v18, v20
	s_nop 0
	v_cndmask_b32_e32 v18, 0, v18, vcc
	v_cmp_nlt_f32_e32 vcc, s73, v15
	s_nop 1
	v_cndmask_b32_e32 v17, v244, v18, vcc
	ds_write2st64_b32 v78, v16, v17 offset0:1 offset1:3
	s_cmp_lg_u32 s0, 0
	s_cbranch_scc1 .LBB0_51
	global_store_dword v1, v12, s[8:9] offset:256
	v_readlane_b32 s2, v254, 55
	v_readlane_b32 s3, v254, 56
	s_nop 0
	s_and_b64 exec, exec, s[2:3]
	s_cbranch_execz .LBB0_51
	s_ashr_i32 s65, s64, 31
	s_lshl_b64 s[2:3], s[64:65], 2
	v_readlane_b32 s1, v254, 57
	s_add_u32 s2, s1, s2
	v_readlane_b32 s1, v254, 58
	s_addc_u32 s3, s1, s3
	s_nop 4
	global_store_dword v113, v13, s[2:3]
